# out-projection epilogue: residual loads hoisted per 4-row batch (2 waits per tile instead of 16), on top of previous best
# speedup vs baseline: 1.0058x; 1.0006x over previous
; DI unsigned cvtpk(float lo, float hi) { typedef float f2 __attribute__((ext_vector_type(2))); typedef __bf16 b2 __attribute__((ext_vector_type(2))); f2 v = {lo, hi}; b2 b = __builtin_convertvector(v, b2); return __builtin_bit_cast(unsigned, b); }
;     DI void operator()(f32x4 (&acc)[2][2][4][2], const pg8::GUnit& u, int wr, int wc, int fr, int fq) const {
;         const int row0 = u.pm * 256 + wr * 64 + fr; const int col0 = u.pn * 256 + wc * 32 + 8 * fq;
; #pragma unroll
;         for (int ai = 0; ai < 2; ++ai)
; #pragma unroll
;             for (int m = 0; m < 4; ++m) {
;                 const int row = row0 + ai * 128 + m * 16;
;                 const size_t off = (size_t)row * DM + col0;
;                 float q = 0.f;
; #pragma unroll
;                 for (int bj = 0; bj < 2; ++bj) {
;                     const f32x4 b0 = *(const f32x4*)(resid + off + bj * 128), b1 = *(const f32x4*)(resid + off + bj * 128 + 4);
;                     const f32x4 v0 = b0 + acc[ai][bj][m][0], v1 = b1 + acc[ai][bj][m][1];
;                     *(f32x4*)(out + off + bj * 128) = v0; *(f32x4*)(out + off + bj * 128 + 4) = v1;
;                     q += (v0[0] * v0[0] + v0[1] * v0[1]) + (v0[2] * v0[2] + v0[3] * v0[3]) + (v1[0] * v1[0] + v1[1] * v1[1]) + (v1[2] * v1[2] + v1[3] * v1[3]);
;                     if (!last) { u32x4 w; w.x = cvtpk(v0[0], v0[1]); w.y = cvtpk(v0[2], v0[3]); w.z = cvtpk(v1[0], v1[1]); w.w = cvtpk(v1[2], v1[3]);
;                         *(u32x4*)(act + (size_t)row * PITCH + XB_COL + col0 + bj * 128) = w; }
;                 }
;                 q += __shfl_xor(q, 16); q += __shfl_xor(q, 32);
;                 if (fq == 0) ssq[(size_t)row * 16 + u.pn * 4 + wc] = q;
;             }
;     }
.LBB0_805:
	v_lshl_add_u32 v142, s55, 8, v150
	v_lshl_or_b32 v140, s38, 8, v152
	v_mov_b32_e32 v145, 0
	v_readlane_b32 s44, v249, 4
	v_readlane_b32 s45, v249, 5
	s_lshl_b32 s22, s38, 4
	s_lshl_b32 s23, s50, 2
	s_add_i32 s23, s23, s22
	v_mov_b32_e32 v143, v142
	v_lshl_add_u32 v144, v143, 10, v140
	v_lshlrev_b32_e32 v144, 2, v144
	v_lshl_add_u64 v[146:147], s[12:13], 0, v[144:145]
	global_load_dwordx4 v[154:157], v[146:147], off nt
	global_load_dwordx4 v[158:161], v[146:147], off offset:16 nt
	global_load_dwordx4 v[162:165], v[146:147], off offset:512 nt
	global_load_dwordx4 v[166:169], v[146:147], off offset:528 nt
	v_or_b32_e32 v143, 16, v142
	v_lshl_add_u32 v144, v143, 10, v140
	v_lshlrev_b32_e32 v144, 2, v144
	v_lshl_add_u64 v[146:147], s[12:13], 0, v[144:145]
	global_load_dwordx4 v[170:173], v[146:147], off nt
	global_load_dwordx4 v[174:177], v[146:147], off offset:16 nt
	global_load_dwordx4 v[178:181], v[146:147], off offset:512 nt
	global_load_dwordx4 v[182:185], v[146:147], off offset:528 nt
	v_or_b32_e32 v143, 32, v142
	v_lshl_add_u32 v144, v143, 10, v140
	v_lshlrev_b32_e32 v144, 2, v144
	v_lshl_add_u64 v[146:147], s[12:13], 0, v[144:145]
	global_load_dwordx4 v[186:189], v[146:147], off nt
	global_load_dwordx4 v[190:193], v[146:147], off offset:16 nt
	global_load_dwordx4 v[206:209], v[146:147], off offset:512 nt
	global_load_dwordx4 v[210:213], v[146:147], off offset:528 nt
	v_or_b32_e32 v143, 48, v142
	v_lshl_add_u32 v144, v143, 10, v140
	v_lshlrev_b32_e32 v144, 2, v144
	v_lshl_add_u64 v[146:147], s[12:13], 0, v[144:145]
	global_load_dwordx4 v[214:217], v[146:147], off nt
	global_load_dwordx4 v[218:221], v[146:147], off offset:16 nt
	global_load_dwordx4 v[222:225], v[146:147], off offset:512 nt
	global_load_dwordx4 v[240:243], v[146:147], off offset:528 nt
	s_waitcnt vmcnt(0)
	v_mov_b32_e32 v143, v142
	v_lshl_add_u32 v144, v143, 10, v140
	v_lshlrev_b32_e32 v144, 2, v144
	v_lshl_add_u64 v[146:147], s[84:85], 0, v[144:145]
	v_add_f32_e32 v126, v126, v154
	v_add_f32_e32 v127, v127, v155
	v_add_f32_e32 v128, v128, v156
	v_add_f32_e32 v129, v129, v157
	v_add_f32_e32 v122, v122, v158
	v_add_f32_e32 v123, v123, v159
	v_add_f32_e32 v124, v124, v160
	v_add_f32_e32 v125, v125, v161
	v_add_f32_e32 v118, v118, v162
	v_add_f32_e32 v119, v119, v163
	v_add_f32_e32 v120, v120, v164
	v_add_f32_e32 v121, v121, v165
	v_add_f32_e32 v114, v114, v166
	v_add_f32_e32 v115, v115, v167
	v_add_f32_e32 v116, v116, v168
	v_add_f32_e32 v117, v117, v169
	global_store_dwordx4 v[146:147], v[126:129], off nt
	global_store_dwordx4 v[146:147], v[122:125], off offset:16 nt
	global_store_dwordx4 v[146:147], v[118:121], off offset:512 nt
	global_store_dwordx4 v[146:147], v[114:117], off offset:528 nt
	s_and_b64 vcc, exec, s[44:45]
	s_cbranch_vccz .Lepo_skip_0
	v_mul_u32_u24_e32 v144, 0x3200, v143
	v_lshl_add_u32 v144, v140, 1, v144
	v_add_u32_e32 v144, 0x2000, v144
	v_lshl_add_u64 v[148:149], s[6:7], 0, v[144:145]
	v_cvt_pk_bf16_f32 v154, v126, v127
	v_cvt_pk_bf16_f32 v155, v128, v129
	v_cvt_pk_bf16_f32 v156, v122, v123
	v_cvt_pk_bf16_f32 v157, v124, v125
	v_cvt_pk_bf16_f32 v158, v118, v119
	v_cvt_pk_bf16_f32 v159, v120, v121
	v_cvt_pk_bf16_f32 v160, v114, v115
	v_cvt_pk_bf16_f32 v161, v116, v117
	global_store_dwordx4 v[148:149], v[154:157], off offset:2560
	global_store_dwordx4 v[148:149], v[158:161], off offset:2816
.Lepo_skip_0:
	v_mul_f32_e32 v162, v126, v126
	v_mul_f32_e32 v163, v122, v122
	v_mul_f32_e32 v164, v118, v118
	v_mul_f32_e32 v165, v114, v114
	v_fmac_f32_e32 v162, v127, v127
	v_fmac_f32_e32 v163, v123, v123
	v_fmac_f32_e32 v164, v119, v119
	v_fmac_f32_e32 v165, v115, v115
	v_fmac_f32_e32 v162, v128, v128
	v_fmac_f32_e32 v163, v124, v124
	v_fmac_f32_e32 v164, v120, v120
	v_fmac_f32_e32 v165, v116, v116
	v_fmac_f32_e32 v162, v129, v129
	v_fmac_f32_e32 v163, v125, v125
	v_fmac_f32_e32 v164, v121, v121
	v_fmac_f32_e32 v165, v117, v117
	v_xor_b32_e32 v166, 16, v227
	v_xor_b32_e32 v167, 32, v227
	v_add_f32_e32 v162, v162, v163
	v_add_f32_e32 v164, v164, v165
	v_lshlrev_b32_e32 v166, 2, v166
	v_lshlrev_b32_e32 v167, 2, v167
	v_add_f32_e32 v162, v162, v164
	ds_bpermute_b32 v163, v166, v162
	s_waitcnt lgkmcnt(0)
	v_add_f32_e32 v162, v162, v163
	ds_bpermute_b32 v163, v167, v162
	v_lshl_add_u32 v144, v143, 6, s23
	v_lshl_add_u64 v[148:149], s[10:11], 0, v[144:145]
	s_waitcnt lgkmcnt(0)
	v_add_f32_e32 v162, v162, v163
	s_and_saveexec_b64 s[24:25], s[40:41]
	global_store_dword v[148:149], v162, off
	s_or_b64 exec, exec, s[24:25]
	v_or_b32_e32 v143, 128, v142
	v_lshl_add_u32 v144, v143, 10, v140
	v_lshlrev_b32_e32 v144, 2, v144
	v_lshl_add_u64 v[146:147], s[12:13], 0, v[144:145]
	global_load_dwordx4 v[154:157], v[146:147], off nt
	global_load_dwordx4 v[158:161], v[146:147], off offset:16 nt
	global_load_dwordx4 v[162:165], v[146:147], off offset:512 nt
	global_load_dwordx4 v[166:169], v[146:147], off offset:528 nt
	v_or_b32_e32 v143, 16, v142
	v_lshl_add_u32 v144, v143, 10, v140
	v_lshlrev_b32_e32 v144, 2, v144
	v_lshl_add_u64 v[146:147], s[84:85], 0, v[144:145]
	v_add_f32_e32 v110, v110, v170
	v_add_f32_e32 v111, v111, v171
	v_add_f32_e32 v112, v112, v172
	v_add_f32_e32 v113, v113, v173
	v_add_f32_e32 v106, v106, v174
	v_add_f32_e32 v107, v107, v175
	v_add_f32_e32 v108, v108, v176
	v_add_f32_e32 v109, v109, v177
	v_add_f32_e32 v102, v102, v178
	v_add_f32_e32 v103, v103, v179
	v_add_f32_e32 v104, v104, v180
	v_add_f32_e32 v105, v105, v181
	v_add_f32_e32 v98, v98, v182
	v_add_f32_e32 v99, v99, v183
	v_add_f32_e32 v100, v100, v184
	v_add_f32_e32 v101, v101, v185
	global_store_dwordx4 v[146:147], v[110:113], off nt
	global_store_dwordx4 v[146:147], v[106:109], off offset:16 nt
	global_store_dwordx4 v[146:147], v[102:105], off offset:512 nt
	global_store_dwordx4 v[146:147], v[98:101], off offset:528 nt
	s_and_b64 vcc, exec, s[44:45]
	s_cbranch_vccz .Lepo_skip_1
	v_mul_u32_u24_e32 v144, 0x3200, v143
	v_lshl_add_u32 v144, v140, 1, v144
	v_add_u32_e32 v144, 0x2000, v144
	v_lshl_add_u64 v[148:149], s[6:7], 0, v[144:145]
	v_cvt_pk_bf16_f32 v170, v110, v111
	v_cvt_pk_bf16_f32 v171, v112, v113
	v_cvt_pk_bf16_f32 v172, v106, v107
	v_cvt_pk_bf16_f32 v173, v108, v109
	v_cvt_pk_bf16_f32 v174, v102, v103
	v_cvt_pk_bf16_f32 v175, v104, v105
	v_cvt_pk_bf16_f32 v176, v98, v99
	v_cvt_pk_bf16_f32 v177, v100, v101
	global_store_dwordx4 v[148:149], v[170:173], off offset:2560
	global_store_dwordx4 v[148:149], v[174:177], off offset:2816
; DI unsigned cvtpk(float lo, float hi) { typedef float f2 __attribute__((ext_vector_type(2))); typedef __bf16 b2 __attribute__((ext_vector_type(2))); f2 v = {lo, hi}; b2 b = __builtin_convertvector(v, b2); return __builtin_bit_cast(unsigned, b); }
;     DI void operator()(f32x4 (&acc)[2][2][4][2], const pg8::GUnit& u, int wr, int wc, int fr, int fq) const {
;         const int row0 = u.pm * 256 + wr * 64 + fr; const int col0 = u.pn * 256 + wc * 32 + 8 * fq;
; #pragma unroll
;         for (int ai = 0; ai < 2; ++ai)
; #pragma unroll
;             for (int m = 0; m < 4; ++m) {
;                 const int row = row0 + ai * 128 + m * 16;
;                 const size_t off = (size_t)row * DM + col0;
;                 float q = 0.f;
; #pragma unroll
;                 for (int bj = 0; bj < 2; ++bj) {
;                     const f32x4 b0 = *(const f32x4*)(resid + off + bj * 128), b1 = *(const f32x4*)(resid + off + bj * 128 + 4);
;                     const f32x4 v0 = b0 + acc[ai][bj][m][0], v1 = b1 + acc[ai][bj][m][1];
;                     *(f32x4*)(out + off + bj * 128) = v0; *(f32x4*)(out + off + bj * 128 + 4) = v1;
;                     q += (v0[0] * v0[0] + v0[1] * v0[1]) + (v0[2] * v0[2] + v0[3] * v0[3]) + (v1[0] * v1[0] + v1[1] * v1[1]) + (v1[2] * v1[2] + v1[3] * v1[3]);
;                     if (!last) { u32x4 w; w.x = cvtpk(v0[0], v0[1]); w.y = cvtpk(v0[2], v0[3]); w.z = cvtpk(v1[0], v1[1]); w.w = cvtpk(v1[2], v1[3]);
;                         *(u32x4*)(act + (size_t)row * PITCH + XB_COL + col0 + bj * 128) = w; }
;                 }
;                 q += __shfl_xor(q, 16); q += __shfl_xor(q, 32);
;                 if (fq == 0) ssq[(size_t)row * 16 + u.pn * 4 + wc] = q;
;             }
;     }
.Lepo_skip_1:
	v_mul_f32_e32 v178, v110, v110
	v_mul_f32_e32 v179, v106, v106
	v_mul_f32_e32 v180, v102, v102
	v_mul_f32_e32 v181, v98, v98
	v_fmac_f32_e32 v178, v111, v111
	v_fmac_f32_e32 v179, v107, v107
	v_fmac_f32_e32 v180, v103, v103
	v_fmac_f32_e32 v181, v99, v99
	v_fmac_f32_e32 v178, v112, v112
	v_fmac_f32_e32 v179, v108, v108
	v_fmac_f32_e32 v180, v104, v104
	v_fmac_f32_e32 v181, v100, v100
	v_fmac_f32_e32 v178, v113, v113
	v_fmac_f32_e32 v179, v109, v109
	v_fmac_f32_e32 v180, v105, v105
	v_fmac_f32_e32 v181, v101, v101
	v_xor_b32_e32 v182, 16, v227
	v_xor_b32_e32 v183, 32, v227
	v_add_f32_e32 v178, v178, v179
	v_add_f32_e32 v180, v180, v181
	v_lshlrev_b32_e32 v182, 2, v182
	v_lshlrev_b32_e32 v183, 2, v183
	v_add_f32_e32 v178, v178, v180
	ds_bpermute_b32 v179, v182, v178
	s_waitcnt lgkmcnt(0)
	v_add_f32_e32 v178, v178, v179
	ds_bpermute_b32 v179, v183, v178
	v_lshl_add_u32 v144, v143, 6, s23
	v_lshl_add_u64 v[148:149], s[10:11], 0, v[144:145]
	s_waitcnt lgkmcnt(0)
	v_add_f32_e32 v178, v178, v179
	s_and_saveexec_b64 s[24:25], s[40:41]
	global_store_dword v[148:149], v178, off
	s_or_b64 exec, exec, s[24:25]
	v_or_b32_e32 v143, 144, v142
	v_lshl_add_u32 v144, v143, 10, v140
	v_lshlrev_b32_e32 v144, 2, v144
	v_lshl_add_u64 v[146:147], s[12:13], 0, v[144:145]
	global_load_dwordx4 v[170:173], v[146:147], off nt
	global_load_dwordx4 v[174:177], v[146:147], off offset:16 nt
	global_load_dwordx4 v[178:181], v[146:147], off offset:512 nt
	global_load_dwordx4 v[182:185], v[146:147], off offset:528 nt
	v_or_b32_e32 v143, 32, v142
	v_lshl_add_u32 v144, v143, 10, v140
	v_lshlrev_b32_e32 v144, 2, v144
	v_lshl_add_u64 v[146:147], s[84:85], 0, v[144:145]
	v_add_f32_e32 v94, v94, v186
	v_add_f32_e32 v95, v95, v187
	v_add_f32_e32 v96, v96, v188
	v_add_f32_e32 v97, v97, v189
	v_add_f32_e32 v90, v90, v190
	v_add_f32_e32 v91, v91, v191
	v_add_f32_e32 v92, v92, v192
	v_add_f32_e32 v93, v93, v193
	v_add_f32_e32 v86, v86, v206
	v_add_f32_e32 v87, v87, v207
	v_add_f32_e32 v88, v88, v208
	v_add_f32_e32 v89, v89, v209
	v_add_f32_e32 v82, v82, v210
	v_add_f32_e32 v83, v83, v211
	v_add_f32_e32 v84, v84, v212
	v_add_f32_e32 v85, v85, v213
	global_store_dwordx4 v[146:147], v[94:97], off nt
	global_store_dwordx4 v[146:147], v[90:93], off offset:16 nt
	global_store_dwordx4 v[146:147], v[86:89], off offset:512 nt
	global_store_dwordx4 v[146:147], v[82:85], off offset:528 nt
	s_and_b64 vcc, exec, s[44:45]
	s_cbranch_vccz .Lepo_skip_2
	v_mul_u32_u24_e32 v144, 0x3200, v143
	v_lshl_add_u32 v144, v140, 1, v144
	v_add_u32_e32 v144, 0x2000, v144
	v_lshl_add_u64 v[148:149], s[6:7], 0, v[144:145]
	v_cvt_pk_bf16_f32 v186, v94, v95
	v_cvt_pk_bf16_f32 v187, v96, v97
	v_cvt_pk_bf16_f32 v188, v90, v91
	v_cvt_pk_bf16_f32 v189, v92, v93
	v_cvt_pk_bf16_f32 v190, v86, v87
	v_cvt_pk_bf16_f32 v191, v88, v89
	v_cvt_pk_bf16_f32 v192, v82, v83
	v_cvt_pk_bf16_f32 v193, v84, v85
	global_store_dwordx4 v[148:149], v[186:189], off offset:2560
	global_store_dwordx4 v[148:149], v[190:193], off offset:2816
.Lepo_skip_2:
	v_mul_f32_e32 v206, v94, v94
	v_mul_f32_e32 v207, v90, v90
	v_mul_f32_e32 v208, v86, v86
	v_mul_f32_e32 v209, v82, v82
	v_fmac_f32_e32 v206, v95, v95
	v_fmac_f32_e32 v207, v91, v91
	v_fmac_f32_e32 v208, v87, v87
	v_fmac_f32_e32 v209, v83, v83
	v_fmac_f32_e32 v206, v96, v96
	v_fmac_f32_e32 v207, v92, v92
	v_fmac_f32_e32 v208, v88, v88
	v_fmac_f32_e32 v209, v84, v84
	v_fmac_f32_e32 v206, v97, v97
	v_fmac_f32_e32 v207, v93, v93
	v_fmac_f32_e32 v208, v89, v89
	v_fmac_f32_e32 v209, v85, v85
	v_xor_b32_e32 v210, 16, v227
	v_xor_b32_e32 v211, 32, v227
	v_add_f32_e32 v206, v206, v207
	v_add_f32_e32 v208, v208, v209
	v_lshlrev_b32_e32 v210, 2, v210
	v_lshlrev_b32_e32 v211, 2, v211
	v_add_f32_e32 v206, v206, v208
	ds_bpermute_b32 v207, v210, v206
	s_waitcnt lgkmcnt(0)
	v_add_f32_e32 v206, v206, v207
	ds_bpermute_b32 v207, v211, v206
	v_lshl_add_u32 v144, v143, 6, s23
	v_lshl_add_u64 v[148:149], s[10:11], 0, v[144:145]
	s_waitcnt lgkmcnt(0)
	v_add_f32_e32 v206, v206, v207
	s_and_saveexec_b64 s[24:25], s[40:41]
	global_store_dword v[148:149], v206, off
	s_or_b64 exec, exec, s[24:25]
	v_or_b32_e32 v143, 160, v142
	v_lshl_add_u32 v144, v143, 10, v140
	v_lshlrev_b32_e32 v144, 2, v144
	v_lshl_add_u64 v[146:147], s[12:13], 0, v[144:145]
	global_load_dwordx4 v[186:189], v[146:147], off nt
	global_load_dwordx4 v[190:193], v[146:147], off offset:16 nt
	global_load_dwordx4 v[206:209], v[146:147], off offset:512 nt
	global_load_dwordx4 v[210:213], v[146:147], off offset:528 nt
	v_or_b32_e32 v143, 48, v142
	v_lshl_add_u32 v144, v143, 10, v140
	v_lshlrev_b32_e32 v144, 2, v144
	v_lshl_add_u64 v[146:147], s[84:85], 0, v[144:145]
	v_add_f32_e32 v78, v78, v214
	v_add_f32_e32 v79, v79, v215
	v_add_f32_e32 v80, v80, v216
	v_add_f32_e32 v81, v81, v217
	v_add_f32_e32 v74, v74, v218
	v_add_f32_e32 v75, v75, v219
	v_add_f32_e32 v76, v76, v220
	v_add_f32_e32 v77, v77, v221
	v_add_f32_e32 v70, v70, v222
	v_add_f32_e32 v71, v71, v223
	v_add_f32_e32 v72, v72, v224
	v_add_f32_e32 v73, v73, v225
	v_add_f32_e32 v66, v66, v240
	v_add_f32_e32 v67, v67, v241
	v_add_f32_e32 v68, v68, v242
	v_add_f32_e32 v69, v69, v243
	global_store_dwordx4 v[146:147], v[78:81], off nt
	global_store_dwordx4 v[146:147], v[74:77], off offset:16 nt
	global_store_dwordx4 v[146:147], v[70:73], off offset:512 nt
	global_store_dwordx4 v[146:147], v[66:69], off offset:528 nt
	s_and_b64 vcc, exec, s[44:45]
	s_cbranch_vccz .Lepo_skip_3
	v_mul_u32_u24_e32 v144, 0x3200, v143
	v_lshl_add_u32 v144, v140, 1, v144
	v_add_u32_e32 v144, 0x2000, v144
	v_lshl_add_u64 v[148:149], s[6:7], 0, v[144:145]
	v_cvt_pk_bf16_f32 v214, v78, v79
	v_cvt_pk_bf16_f32 v215, v80, v81
	v_cvt_pk_bf16_f32 v216, v74, v75
	v_cvt_pk_bf16_f32 v217, v76, v77
	v_cvt_pk_bf16_f32 v218, v70, v71
	v_cvt_pk_bf16_f32 v219, v72, v73
	v_cvt_pk_bf16_f32 v220, v66, v67
	v_cvt_pk_bf16_f32 v221, v68, v69
	global_store_dwordx4 v[148:149], v[214:217], off offset:2560
	global_store_dwordx4 v[148:149], v[218:221], off offset:2816
; DI unsigned cvtpk(float lo, float hi) { typedef float f2 __attribute__((ext_vector_type(2))); typedef __bf16 b2 __attribute__((ext_vector_type(2))); f2 v = {lo, hi}; b2 b = __builtin_convertvector(v, b2); return __builtin_bit_cast(unsigned, b); }
;     DI void operator()(f32x4 (&acc)[2][2][4][2], const pg8::GUnit& u, int wr, int wc, int fr, int fq) const {
;         const int row0 = u.pm * 256 + wr * 64 + fr; const int col0 = u.pn * 256 + wc * 32 + 8 * fq;
; #pragma unroll
;         for (int ai = 0; ai < 2; ++ai)
; #pragma unroll
;             for (int m = 0; m < 4; ++m) {
;                 const int row = row0 + ai * 128 + m * 16;
;                 const size_t off = (size_t)row * DM + col0;
;                 float q = 0.f;
; #pragma unroll
;                 for (int bj = 0; bj < 2; ++bj) {
;                     const f32x4 b0 = *(const f32x4*)(resid + off + bj * 128), b1 = *(const f32x4*)(resid + off + bj * 128 + 4);
;                     const f32x4 v0 = b0 + acc[ai][bj][m][0], v1 = b1 + acc[ai][bj][m][1];
;                     *(f32x4*)(out + off + bj * 128) = v0; *(f32x4*)(out + off + bj * 128 + 4) = v1;
;                     q += (v0[0] * v0[0] + v0[1] * v0[1]) + (v0[2] * v0[2] + v0[3] * v0[3]) + (v1[0] * v1[0] + v1[1] * v1[1]) + (v1[2] * v1[2] + v1[3] * v1[3]);
;                     if (!last) { u32x4 w; w.x = cvtpk(v0[0], v0[1]); w.y = cvtpk(v0[2], v0[3]); w.z = cvtpk(v1[0], v1[1]); w.w = cvtpk(v1[2], v1[3]);
;                         *(u32x4*)(act + (size_t)row * PITCH + XB_COL + col0 + bj * 128) = w; }
;                 }
;                 q += __shfl_xor(q, 16); q += __shfl_xor(q, 32);
;                 if (fq == 0) ssq[(size_t)row * 16 + u.pn * 4 + wc] = q;
;             }
;     }
.Lepo_skip_3:
	v_mul_f32_e32 v222, v78, v78
	v_mul_f32_e32 v223, v74, v74
	v_mul_f32_e32 v224, v70, v70
	v_mul_f32_e32 v225, v66, v66
	v_fmac_f32_e32 v222, v79, v79
	v_fmac_f32_e32 v223, v75, v75
	v_fmac_f32_e32 v224, v71, v71
	v_fmac_f32_e32 v225, v67, v67
	v_fmac_f32_e32 v222, v80, v80
	v_fmac_f32_e32 v223, v76, v76
	v_fmac_f32_e32 v224, v72, v72
	v_fmac_f32_e32 v225, v68, v68
	v_fmac_f32_e32 v222, v81, v81
	v_fmac_f32_e32 v223, v77, v77
	v_fmac_f32_e32 v224, v73, v73
	v_fmac_f32_e32 v225, v69, v69
	v_xor_b32_e32 v240, 16, v227
	v_xor_b32_e32 v241, 32, v227
	v_add_f32_e32 v222, v222, v223
	v_add_f32_e32 v224, v224, v225
	v_lshlrev_b32_e32 v240, 2, v240
	v_lshlrev_b32_e32 v241, 2, v241
	v_add_f32_e32 v222, v222, v224
	ds_bpermute_b32 v223, v240, v222
	s_waitcnt lgkmcnt(0)
	v_add_f32_e32 v222, v222, v223
	ds_bpermute_b32 v223, v241, v222
	v_lshl_add_u32 v144, v143, 6, s23
	v_lshl_add_u64 v[148:149], s[10:11], 0, v[144:145]
	s_waitcnt lgkmcnt(0)
	v_add_f32_e32 v222, v222, v223
	s_and_saveexec_b64 s[24:25], s[40:41]
	global_store_dword v[148:149], v222, off
	s_or_b64 exec, exec, s[24:25]
	v_or_b32_e32 v143, 176, v142
	v_lshl_add_u32 v144, v143, 10, v140
	v_lshlrev_b32_e32 v144, 2, v144
	v_lshl_add_u64 v[146:147], s[12:13], 0, v[144:145]
	global_load_dwordx4 v[214:217], v[146:147], off nt
	global_load_dwordx4 v[218:221], v[146:147], off offset:16 nt
	global_load_dwordx4 v[222:225], v[146:147], off offset:512 nt
	global_load_dwordx4 v[240:243], v[146:147], off offset:528 nt
	s_waitcnt vmcnt(0)
	v_or_b32_e32 v143, 128, v142
	v_lshl_add_u32 v144, v143, 10, v140
	v_lshlrev_b32_e32 v144, 2, v144
	v_lshl_add_u64 v[146:147], s[84:85], 0, v[144:145]
	v_add_f32_e32 v62, v62, v154
	v_add_f32_e32 v63, v63, v155
	v_add_f32_e32 v64, v64, v156
	v_add_f32_e32 v65, v65, v157
	v_add_f32_e32 v58, v58, v158
	v_add_f32_e32 v59, v59, v159
	v_add_f32_e32 v60, v60, v160
	v_add_f32_e32 v61, v61, v161
	v_add_f32_e32 v54, v54, v162
	v_add_f32_e32 v55, v55, v163
	v_add_f32_e32 v56, v56, v164
	v_add_f32_e32 v57, v57, v165
	v_add_f32_e32 v50, v50, v166
	v_add_f32_e32 v51, v51, v167
	v_add_f32_e32 v52, v52, v168
	v_add_f32_e32 v53, v53, v169
	global_store_dwordx4 v[146:147], v[62:65], off nt
	global_store_dwordx4 v[146:147], v[58:61], off offset:16 nt
	global_store_dwordx4 v[146:147], v[54:57], off offset:512 nt
	global_store_dwordx4 v[146:147], v[50:53], off offset:528 nt
	s_and_b64 vcc, exec, s[44:45]
	s_cbranch_vccz .Lepo_skip_4
	v_mul_u32_u24_e32 v144, 0x3200, v143
	v_lshl_add_u32 v144, v140, 1, v144
	v_add_u32_e32 v144, 0x2000, v144
	v_lshl_add_u64 v[148:149], s[6:7], 0, v[144:145]
	v_cvt_pk_bf16_f32 v154, v62, v63
	v_cvt_pk_bf16_f32 v155, v64, v65
	v_cvt_pk_bf16_f32 v156, v58, v59
	v_cvt_pk_bf16_f32 v157, v60, v61
	v_cvt_pk_bf16_f32 v158, v54, v55
	v_cvt_pk_bf16_f32 v159, v56, v57
	v_cvt_pk_bf16_f32 v160, v50, v51
	v_cvt_pk_bf16_f32 v161, v52, v53
	global_store_dwordx4 v[148:149], v[154:157], off offset:2560
	global_store_dwordx4 v[148:149], v[158:161], off offset:2816
.Lepo_skip_4:
	v_mul_f32_e32 v162, v62, v62
	v_mul_f32_e32 v163, v58, v58
	v_mul_f32_e32 v164, v54, v54
	v_mul_f32_e32 v165, v50, v50
	v_fmac_f32_e32 v162, v63, v63
	v_fmac_f32_e32 v163, v59, v59
	v_fmac_f32_e32 v164, v55, v55
	v_fmac_f32_e32 v165, v51, v51
	v_fmac_f32_e32 v162, v64, v64
	v_fmac_f32_e32 v163, v60, v60
	v_fmac_f32_e32 v164, v56, v56
	v_fmac_f32_e32 v165, v52, v52
	v_fmac_f32_e32 v162, v65, v65
	v_fmac_f32_e32 v163, v61, v61
	v_fmac_f32_e32 v164, v57, v57
	v_fmac_f32_e32 v165, v53, v53
	v_xor_b32_e32 v166, 16, v227
	v_xor_b32_e32 v167, 32, v227
	v_add_f32_e32 v162, v162, v163
	v_add_f32_e32 v164, v164, v165
	v_lshlrev_b32_e32 v166, 2, v166
	v_lshlrev_b32_e32 v167, 2, v167
	v_add_f32_e32 v162, v162, v164
	ds_bpermute_b32 v163, v166, v162
	s_waitcnt lgkmcnt(0)
	v_add_f32_e32 v162, v162, v163
	ds_bpermute_b32 v163, v167, v162
	v_lshl_add_u32 v144, v143, 6, s23
	v_lshl_add_u64 v[148:149], s[10:11], 0, v[144:145]
	s_waitcnt lgkmcnt(0)
	v_add_f32_e32 v162, v162, v163
	s_and_saveexec_b64 s[24:25], s[40:41]
	global_store_dword v[148:149], v162, off
	s_or_b64 exec, exec, s[24:25]
	v_or_b32_e32 v143, 144, v142
	v_lshl_add_u32 v144, v143, 10, v140
	v_lshlrev_b32_e32 v144, 2, v144
	v_lshl_add_u64 v[146:147], s[84:85], 0, v[144:145]
	v_add_f32_e32 v46, v46, v170
	v_add_f32_e32 v47, v47, v171
	v_add_f32_e32 v48, v48, v172
	v_add_f32_e32 v49, v49, v173
	v_add_f32_e32 v42, v42, v174
	v_add_f32_e32 v43, v43, v175
	v_add_f32_e32 v44, v44, v176
	v_add_f32_e32 v45, v45, v177
	v_add_f32_e32 v38, v38, v178
	v_add_f32_e32 v39, v39, v179
	v_add_f32_e32 v40, v40, v180
	v_add_f32_e32 v41, v41, v181
	v_add_f32_e32 v34, v34, v182
	v_add_f32_e32 v35, v35, v183
	v_add_f32_e32 v36, v36, v184
	v_add_f32_e32 v37, v37, v185
	global_store_dwordx4 v[146:147], v[46:49], off nt
	global_store_dwordx4 v[146:147], v[42:45], off offset:16 nt
	global_store_dwordx4 v[146:147], v[38:41], off offset:512 nt
	global_store_dwordx4 v[146:147], v[34:37], off offset:528 nt
	s_and_b64 vcc, exec, s[44:45]
	s_cbranch_vccz .Lepo_skip_5
	v_mul_u32_u24_e32 v144, 0x3200, v143
	v_lshl_add_u32 v144, v140, 1, v144
	v_add_u32_e32 v144, 0x2000, v144
	v_lshl_add_u64 v[148:149], s[6:7], 0, v[144:145]
	v_cvt_pk_bf16_f32 v170, v46, v47
	v_cvt_pk_bf16_f32 v171, v48, v49
	v_cvt_pk_bf16_f32 v172, v42, v43
	v_cvt_pk_bf16_f32 v173, v44, v45
	v_cvt_pk_bf16_f32 v174, v38, v39
	v_cvt_pk_bf16_f32 v175, v40, v41
	v_cvt_pk_bf16_f32 v176, v34, v35
	v_cvt_pk_bf16_f32 v177, v36, v37
	global_store_dwordx4 v[148:149], v[170:173], off offset:2560
	global_store_dwordx4 v[148:149], v[174:177], off offset:2816
; DI unsigned cvtpk(float lo, float hi) { typedef float f2 __attribute__((ext_vector_type(2))); typedef __bf16 b2 __attribute__((ext_vector_type(2))); f2 v = {lo, hi}; b2 b = __builtin_convertvector(v, b2); return __builtin_bit_cast(unsigned, b); }
;     DI void operator()(f32x4 (&acc)[2][2][4][2], const pg8::GUnit& u, int wr, int wc, int fr, int fq) const {
;         const int row0 = u.pm * 256 + wr * 64 + fr; const int col0 = u.pn * 256 + wc * 32 + 8 * fq;
; #pragma unroll
;         for (int ai = 0; ai < 2; ++ai)
; #pragma unroll
;             for (int m = 0; m < 4; ++m) {
;                 const int row = row0 + ai * 128 + m * 16;
;                 const size_t off = (size_t)row * DM + col0;
;                 float q = 0.f;
; #pragma unroll
;                 for (int bj = 0; bj < 2; ++bj) {
;                     const f32x4 b0 = *(const f32x4*)(resid + off + bj * 128), b1 = *(const f32x4*)(resid + off + bj * 128 + 4);
;                     const f32x4 v0 = b0 + acc[ai][bj][m][0], v1 = b1 + acc[ai][bj][m][1];
;                     *(f32x4*)(out + off + bj * 128) = v0; *(f32x4*)(out + off + bj * 128 + 4) = v1;
;                     q += (v0[0] * v0[0] + v0[1] * v0[1]) + (v0[2] * v0[2] + v0[3] * v0[3]) + (v1[0] * v1[0] + v1[1] * v1[1]) + (v1[2] * v1[2] + v1[3] * v1[3]);
;                     if (!last) { u32x4 w; w.x = cvtpk(v0[0], v0[1]); w.y = cvtpk(v0[2], v0[3]); w.z = cvtpk(v1[0], v1[1]); w.w = cvtpk(v1[2], v1[3]);
;                         *(u32x4*)(act + (size_t)row * PITCH + XB_COL + col0 + bj * 128) = w; }
;                 }
;                 q += __shfl_xor(q, 16); q += __shfl_xor(q, 32);
;                 if (fq == 0) ssq[(size_t)row * 16 + u.pn * 4 + wc] = q;
;             }
;     }
.Lepo_skip_5:
	v_mul_f32_e32 v178, v46, v46
	v_mul_f32_e32 v179, v42, v42
	v_mul_f32_e32 v180, v38, v38
	v_mul_f32_e32 v181, v34, v34
	v_fmac_f32_e32 v178, v47, v47
	v_fmac_f32_e32 v179, v43, v43
	v_fmac_f32_e32 v180, v39, v39
	v_fmac_f32_e32 v181, v35, v35
	v_fmac_f32_e32 v178, v48, v48
	v_fmac_f32_e32 v179, v44, v44
	v_fmac_f32_e32 v180, v40, v40
	v_fmac_f32_e32 v181, v36, v36
	v_fmac_f32_e32 v178, v49, v49
	v_fmac_f32_e32 v179, v45, v45
	v_fmac_f32_e32 v180, v41, v41
	v_fmac_f32_e32 v181, v37, v37
	v_xor_b32_e32 v182, 16, v227
	v_xor_b32_e32 v183, 32, v227
	v_add_f32_e32 v178, v178, v179
	v_add_f32_e32 v180, v180, v181
	v_lshlrev_b32_e32 v182, 2, v182
	v_lshlrev_b32_e32 v183, 2, v183
	v_add_f32_e32 v178, v178, v180
	ds_bpermute_b32 v179, v182, v178
	s_waitcnt lgkmcnt(0)
	v_add_f32_e32 v178, v178, v179
	ds_bpermute_b32 v179, v183, v178
	v_lshl_add_u32 v144, v143, 6, s23
	v_lshl_add_u64 v[148:149], s[10:11], 0, v[144:145]
	s_waitcnt lgkmcnt(0)
	v_add_f32_e32 v178, v178, v179
	s_and_saveexec_b64 s[24:25], s[40:41]
	global_store_dword v[148:149], v178, off
	s_or_b64 exec, exec, s[24:25]
	v_or_b32_e32 v143, 160, v142
	v_lshl_add_u32 v144, v143, 10, v140
	v_lshlrev_b32_e32 v144, 2, v144
	v_lshl_add_u64 v[146:147], s[84:85], 0, v[144:145]
	v_add_f32_e32 v30, v30, v186
	v_add_f32_e32 v31, v31, v187
	v_add_f32_e32 v32, v32, v188
	v_add_f32_e32 v33, v33, v189
	v_add_f32_e32 v26, v26, v190
	v_add_f32_e32 v27, v27, v191
	v_add_f32_e32 v28, v28, v192
	v_add_f32_e32 v29, v29, v193
	v_add_f32_e32 v22, v22, v206
	v_add_f32_e32 v23, v23, v207
	v_add_f32_e32 v24, v24, v208
	v_add_f32_e32 v25, v25, v209
	v_add_f32_e32 v18, v18, v210
	v_add_f32_e32 v19, v19, v211
	v_add_f32_e32 v20, v20, v212
	v_add_f32_e32 v21, v21, v213
	global_store_dwordx4 v[146:147], v[30:33], off nt
	global_store_dwordx4 v[146:147], v[26:29], off offset:16 nt
	global_store_dwordx4 v[146:147], v[22:25], off offset:512 nt
	global_store_dwordx4 v[146:147], v[18:21], off offset:528 nt
	s_and_b64 vcc, exec, s[44:45]
	s_cbranch_vccz .Lepo_skip_6
	v_mul_u32_u24_e32 v144, 0x3200, v143
	v_lshl_add_u32 v144, v140, 1, v144
	v_add_u32_e32 v144, 0x2000, v144
	v_lshl_add_u64 v[148:149], s[6:7], 0, v[144:145]
	v_cvt_pk_bf16_f32 v186, v30, v31
	v_cvt_pk_bf16_f32 v187, v32, v33
	v_cvt_pk_bf16_f32 v188, v26, v27
	v_cvt_pk_bf16_f32 v189, v28, v29
	v_cvt_pk_bf16_f32 v190, v22, v23
	v_cvt_pk_bf16_f32 v191, v24, v25
	v_cvt_pk_bf16_f32 v192, v18, v19
	v_cvt_pk_bf16_f32 v193, v20, v21
	global_store_dwordx4 v[148:149], v[186:189], off offset:2560
	global_store_dwordx4 v[148:149], v[190:193], off offset:2816
.Lepo_skip_6:
	v_mul_f32_e32 v206, v30, v30
	v_mul_f32_e32 v207, v26, v26
	v_mul_f32_e32 v208, v22, v22
	v_mul_f32_e32 v209, v18, v18
	v_fmac_f32_e32 v206, v31, v31
	v_fmac_f32_e32 v207, v27, v27
	v_fmac_f32_e32 v208, v23, v23
	v_fmac_f32_e32 v209, v19, v19
	v_fmac_f32_e32 v206, v32, v32
	v_fmac_f32_e32 v207, v28, v28
	v_fmac_f32_e32 v208, v24, v24
	v_fmac_f32_e32 v209, v20, v20
	v_fmac_f32_e32 v206, v33, v33
	v_fmac_f32_e32 v207, v29, v29
	v_fmac_f32_e32 v208, v25, v25
	v_fmac_f32_e32 v209, v21, v21
	v_xor_b32_e32 v210, 16, v227
	v_xor_b32_e32 v211, 32, v227
	v_add_f32_e32 v206, v206, v207
	v_add_f32_e32 v208, v208, v209
	v_lshlrev_b32_e32 v210, 2, v210
	v_lshlrev_b32_e32 v211, 2, v211
	v_add_f32_e32 v206, v206, v208
	ds_bpermute_b32 v207, v210, v206
	s_waitcnt lgkmcnt(0)
	v_add_f32_e32 v206, v206, v207
	ds_bpermute_b32 v207, v211, v206
	v_lshl_add_u32 v144, v143, 6, s23
	v_lshl_add_u64 v[148:149], s[10:11], 0, v[144:145]
	s_waitcnt lgkmcnt(0)
	v_add_f32_e32 v206, v206, v207
	s_and_saveexec_b64 s[24:25], s[40:41]
	global_store_dword v[148:149], v206, off
	s_or_b64 exec, exec, s[24:25]
	v_or_b32_e32 v143, 176, v142
	v_lshl_add_u32 v144, v143, 10, v140
	v_lshlrev_b32_e32 v144, 2, v144
	v_lshl_add_u64 v[146:147], s[84:85], 0, v[144:145]
	v_add_f32_e32 v14, v14, v214
	v_add_f32_e32 v15, v15, v215
	v_add_f32_e32 v16, v16, v216
	v_add_f32_e32 v17, v17, v217
	v_add_f32_e32 v10, v10, v218
	v_add_f32_e32 v11, v11, v219
	v_add_f32_e32 v12, v12, v220
	v_add_f32_e32 v13, v13, v221
	v_add_f32_e32 v6, v6, v222
	v_add_f32_e32 v7, v7, v223
	v_add_f32_e32 v8, v8, v224
	v_add_f32_e32 v9, v9, v225
	v_add_f32_e32 v2, v2, v240
	v_add_f32_e32 v3, v3, v241
	v_add_f32_e32 v4, v4, v242
	v_add_f32_e32 v5, v5, v243
	global_store_dwordx4 v[146:147], v[14:17], off nt
	global_store_dwordx4 v[146:147], v[10:13], off offset:16 nt
	global_store_dwordx4 v[146:147], v[6:9], off offset:512 nt
	global_store_dwordx4 v[146:147], v[2:5], off offset:528 nt
	s_and_b64 vcc, exec, s[44:45]
	s_cbranch_vccz .Lepo_skip_7
	v_mul_u32_u24_e32 v144, 0x3200, v143
	v_lshl_add_u32 v144, v140, 1, v144
	v_add_u32_e32 v144, 0x2000, v144
	v_lshl_add_u64 v[148:149], s[6:7], 0, v[144:145]
	v_cvt_pk_bf16_f32 v214, v14, v15
	v_cvt_pk_bf16_f32 v215, v16, v17
	v_cvt_pk_bf16_f32 v216, v10, v11
	v_cvt_pk_bf16_f32 v217, v12, v13
	v_cvt_pk_bf16_f32 v218, v6, v7
	v_cvt_pk_bf16_f32 v219, v8, v9
	v_cvt_pk_bf16_f32 v220, v2, v3
	v_cvt_pk_bf16_f32 v221, v4, v5
	global_store_dwordx4 v[148:149], v[214:217], off offset:2560
	global_store_dwordx4 v[148:149], v[218:221], off offset:2816
.Lepo_skip_7:
	v_mul_f32_e32 v222, v14, v14
	v_mul_f32_e32 v223, v10, v10
	v_mul_f32_e32 v224, v6, v6
	v_mul_f32_e32 v225, v2, v2
	v_fmac_f32_e32 v222, v15, v15
	v_fmac_f32_e32 v223, v11, v11
	v_fmac_f32_e32 v224, v7, v7
	v_fmac_f32_e32 v225, v3, v3
	v_fmac_f32_e32 v222, v16, v16
	v_fmac_f32_e32 v223, v12, v12
	v_fmac_f32_e32 v224, v8, v8
	v_fmac_f32_e32 v225, v4, v4
	v_fmac_f32_e32 v222, v17, v17
	v_fmac_f32_e32 v223, v13, v13
	v_fmac_f32_e32 v224, v9, v9
	v_fmac_f32_e32 v225, v5, v5
	v_xor_b32_e32 v240, 16, v227
	v_xor_b32_e32 v241, 32, v227
	v_add_f32_e32 v222, v222, v223
	v_add_f32_e32 v224, v224, v225
	v_lshlrev_b32_e32 v240, 2, v240
	v_lshlrev_b32_e32 v241, 2, v241
	v_add_f32_e32 v222, v222, v224
	ds_bpermute_b32 v223, v240, v222
	s_waitcnt lgkmcnt(0)
	v_add_f32_e32 v222, v222, v223
	ds_bpermute_b32 v223, v241, v222
	v_lshl_add_u32 v144, v143, 6, s23
	v_lshl_add_u64 v[148:149], s[10:11], 0, v[144:145]
	s_waitcnt lgkmcnt(0)
	v_add_f32_e32 v222, v222, v223
	s_and_saveexec_b64 s[24:25], s[40:41]
	global_store_dword v[148:149], v222, off
	s_or_b64 exec, exec, s[24:25]
